# grid barriers: arrival-counter poll interval s_sleep 2 -> 16 (256 pollers were contending with the late arrivers' atomics on the same line)
# speedup vs baseline: 1.0315x; 1.0068x over previous
.LBB0_308:
	s_sleep 16
	global_load_dword v1, v0, s[44:45] sc1
	s_waitcnt vmcnt(0)
	v_cmp_gt_u32_e32 vcc, s95, v1
	s_cbranch_vccnz .LBB0_308

.LBB0_694:
	s_sleep 16
	global_load_dword v1, v211, s[44:45] sc1
	s_waitcnt vmcnt(0)
	v_cmp_gt_u32_e32 vcc, s4, v1
	s_cbranch_vccnz .LBB0_694

.LBB0_1196:
	s_sleep 16
	global_load_dword v1, v211, s[44:45] sc1
	s_waitcnt vmcnt(0)
	v_cmp_gt_u32_e32 vcc, s4, v1
	s_cbranch_vccnz .LBB0_1196
	s_getpc_b64 s[98:99]
